# strategy 4: K-loop per-block setprio flips deleted, one static priority raise for waves 4-7 per GEMM phase
# baseline (speedup 1.0000x reference)
; __device__ __forceinline__ int tid_fresh() { int t = threadIdx.x; asm volatile("" : "+v"(t)); return t; }
; #define PG8_STAGE(bufoff, gbase, voff) do { _Pragma("unroll") for (int _i = 0; _i < 2; ++_i) \
;         __builtin_amdgcn_global_load_lds((const unsigned*)((const char*)(gbase) + (voff)[_i]), (LAS unsigned*)(lds + (bufoff) + ldsw + _i * 8192), 16, 0, 0); } while (0)
; #define PG8_WAIT_V(n) asm volatile("s_waitcnt vmcnt(" #n ")" ::: "memory")
; template <class Epi>
; __device__ __forceinline__ void gemm_phase(LAS unsigned char* lds, const Gemm g, const StaticOrder& S, const Epi& E) {
;     const int tid = tid_fresh(), wid = __builtin_amdgcn_readfirstlane(tid >> 6), lane = tid & 63, wr = wid >> 2, wc = wid & 3, fr = lane & 15, fq = lane >> 4;
;     const int K = g.K, nt = K / BK, lda = g.lda;
;     unsigned voffA[2], voffB[2];
; #pragma unroll
;     for (int i = 0; i < 2; ++i) { int R, C; stage_rc(tid * 16 + i * 8192, R, C); const int Rb = Epi::PERM ? ((R & ~31) + perm32(R & 31)) : R;
;         voffA[i] = (unsigned)(R * lda + C) * 2u; voffB[i] = (unsigned)(Rb * K + C) * 2u; }
;     const size_t kstep = (size_t)(BK * 2);
;     const size_t hA = (size_t)HALF * lda * 2, hB = (size_t)HALF * K * 2;
;     const size_t tA = 2 * hA, tB = 2 * hB;
;     const unsigned ldsw = (unsigned)wid * 1024u;
;     const int aoff = lds_byte(wr * 64 + fr, fq * 8), boff = lds_byte(wc * 32 + fr, fq * 8);
;     ...
;     Unit cur, nxt; int ui = 0;
;     if (!S.next(0, cur)) return;
;     f32x4 acc[2][2][4][2];
; #pragma unroll
;     for (int a = 0; a < 2; ++a)
; #pragma unroll
;         for (int b = 0; b < 2; ++b)
; #pragma unroll
;             for (int m = 0; m < 4; ++m)
; #pragma unroll
;                 for (int n = 0; n < 2; ++n) acc[a][b][m][n] = (f32x4){0.f, 0.f, 0.f, 0.f};
;     bf16x8 At[4][2], B0[2][2], B1[2][2];
;     const char* cA = (const char*)g.A + (size_t)cur.pm * tA + (g.agrp ? (size_t)(cur.pn >> 1) * 1024 : 0);
;     const char* cB = (const char*)g.Bt + (size_t)cur.pn * tB;
;     PG8_STAGE(PG8_SB(0, 0), cB, voffB); PG8_STAGE(PG8_SB(0, 1), cB + hB, voffB); PG8_STAGE(PG8_SA(0, 0), cA, voffA); PG8_STAGE(PG8_SA(0, 1), cA + hA, voffA);
;     if (wr == 1) PG8_BAR;
;     PG8_WAIT_V(2); PG8_BAR;
;     PG8_STAGE(PG8_SB(1, 0), cB + kstep, voffB); PG8_STAGE(PG8_SA(1, 0), cA + kstep, voffA); PG8_STAGE(PG8_SB(1, 1), cB + hB + kstep, voffB);
;     PG8_WAIT_V(6); PG8_BAR;
.LBB0_328:
	v_bfe_u32 v19, v15, 4, 2
	v_and_b32_e32 v20, 15, v15
	v_lshlrev_b32_e32 v21, 4, v19
	v_lshlrev_b32_e32 v15, 2, v15
	s_and_b32 s46, s0, 3
	v_lshl_or_b32 v188, s1, 6, v20
	s_cmp_eq_u32 s1, 1
	s_cbranch_scc0 .Lprio_done_1
	s_setprio 1
.Lprio_done_1:
	v_lshl_or_b32 v20, v20, 6, v21
	s_lshl_b32 s0, s1, 13
	v_and_b32_e32 v15, 32, v15
	s_lshr_b32 s47, s7, 6
	v_bitop3_b32 v21, v20, s0, v15 bitop3:0xde
	s_lshl_b32 s0, s46, 12
	s_add_u32 s22, s74, 0x17784000
	s_addc_u32 s23, s75, 0
	s_add_i32 m0, s42, 0x18000
	v_lshl_add_u64 v[0:1], v[0:1], 0, s[80:81]
	s_waitcnt vmcnt(2)
	s_barrier
	global_load_lds_dwordx4 v[0:1], off
	v_lshl_add_u64 v[0:1], v[2:3], 0, s[80:81]
	s_add_i32 m0, s42, 0x1a000
	s_add_i32 s48, s42, 0x8000
	global_load_lds_dwordx4 v[0:1], off
	v_lshl_add_u64 v[0:1], v[8:9], 0, s[80:81]
	s_mov_b32 m0, s48
	s_add_i32 s49, s42, 0xa000
	global_load_lds_dwordx4 v[0:1], off
	v_lshl_add_u64 v[0:1], v[10:11], 0, s[80:81]
	s_mov_b32 m0, s49
	s_add_i32 s50, s47, -2
	global_load_lds_dwordx4 v[0:1], off
	s_add_i32 m0, s42, 0x1c000
	v_lshl_add_u64 v[0:1], v[4:5], 0, s[80:81]
	global_load_lds_dwordx4 v[0:1], off
	v_lshl_add_u64 v[0:1], v[6:7], 0, s[80:81]
	s_add_i32 m0, s42, 0x1e000
	s_cmpk_lt_u32 s6, 0x100
	global_load_lds_dwordx4 v[0:1], off
	v_lshlrev_b32_e32 v0, 2, v19
	v_lshl_or_b32 v190, s46, 5, v0
	v_add_u32_e32 v0, v14, v12
	v_add_lshl_u32 v0, v0, v13, 1
	v_mov_b32_e32 v1, v169
	s_waitcnt vmcnt(6)
	s_cselect_b64 s[24:25], -1, 0
	s_ashr_i32 s52, s39, 31
	s_ashr_i32 s53, s40, 31
	v_lshl_add_u64 v[176:177], s[16:17], 0, v[0:1]
	v_add_u32_e32 v0, v18, v16
	s_cmp_lg_u64 s[10:11], 0
	v_add_lshl_u32 v0, v0, v17, 1
	v_bitop3_b32 v189, v20, s0, v15 bitop3:0xde
	v_add_u32_e32 v240, 0x10000, v189
	v_add_u32_e32 v241, 0x80, v168
	v_add_u32_e32 v242, 0x80, v174
	s_mov_b32 s51, 0
	v_cmp_eq_u32_e64 s[0:1], 0, v19
	s_cselect_b64 s[26:27], -1, 0
	v_lshl_add_u64 v[178:179], s[16:17], 0, v[0:1]
	v_add_u32_e32 v191, 0, v21
	s_barrier
	s_branch .LBB0_331

; #define PG8_STAGE(bufoff, gbase, voff) do { _Pragma("unroll") for (int _i = 0; _i < 2; ++_i) \
;         __builtin_amdgcn_global_load_lds((const unsigned*)((const char*)(gbase) + (voff)[_i]), (LAS unsigned*)(lds + (bufoff) + ldsw + _i * 8192), 16, 0, 0); } while (0)
; #define PG8_LDA(dst, b, h) do { _Pragma("unroll") for (int m = 0; m < 4; ++m) _Pragma("unroll") for (int k = 0; k < 2; ++k) dst[m][k] = *(const LAS bf16x8*)(lds + PG8_SA(b, h) + aoff + m * 2048 + k * 1024); } while (0)
; #define PG8_LDB(dst, b, h) do { _Pragma("unroll") for (int n = 0; n < 2; ++n) _Pragma("unroll") for (int k = 0; k < 2; ++k) dst[n][k] = *(const LAS bf16x8*)(lds + PG8_SB(b, h) + boff + n * 2048 + k * 1024); } while (0)
; #define PG8_MMA(ai, bj, At, Bt) do { __builtin_amdgcn_s_setprio(1); _Pragma("unroll") for (int m = 0; m < 4; ++m) _Pragma("unroll") for (int n = 0; n < 2; ++n) _Pragma("unroll") for (int k = 0; k < 2; ++k) \
;         acc[ai][bj][m][n] = __builtin_amdgcn_mfma_f32_16x16x32_bf16(Bt[n][k], At[m][k], acc[ai][bj][m][n], 0, 0, 0); __builtin_amdgcn_s_setprio(0); } while (0)
; #define PG8_WAIT_V(n) asm volatile("s_waitcnt vmcnt(" #n ")" ::: "memory")
; #define PG8_WAIT_L(n) asm volatile("s_waitcnt lgkmcnt(" #n ")" ::: "memory")
; #define PG8_BAR __builtin_amdgcn_s_barrier()
; #define PG8_SCHED __builtin_amdgcn_sched_barrier(0)
; template <class Epi>
; __device__ __forceinline__ void gemm_phase(LAS unsigned char* lds, const Gemm g, const StaticOrder& S, const Epi& E) {
;     ...
;         for (int t = 0; t < nt; t += 2) {
;             const bool last = (t == nt - 2);
;             const char* a1 = cA + (size_t)(t + 1) * kstep;
;             const char* a2 = last ? nA : cA + (size_t)(t + 2) * kstep; const char* b2 = last ? nB : cB + (size_t)(t + 2) * kstep;
;             const char* a3 = a2 + kstep; const char* b3 = b2 + kstep;
;             PG8_LDB(B0, 0, 0); PG8_LDB(B1, 0, 1); PG8_SCHED; PG8_LDA(At, 0, 0); PG8_STAGE(PG8_SA(1, 1), a1 + hA, voffA);
;             PG8_WAIT_V(8); PG8_WAIT_L(0); PG8_BAR; PG8_MMA(0, 0, At, B0); PG8_MMA(0, 1, At, B1); PG8_BAR; PG8_SCHED;
;             PG8_LDA(At, 0, 1); PG8_STAGE(PG8_SB(0, 0), b2, voffB); PG8_STAGE(PG8_SB(0, 1), b2 + hB, voffB); PG8_STAGE(PG8_SA(0, 0), a2, voffA);
;             PG8_WAIT_V(8); PG8_WAIT_L(0); PG8_BAR; PG8_MMA(1, 0, At, B0); PG8_MMA(1, 1, At, B1); PG8_BAR; PG8_SCHED;
.LBB0_342:
	s_add_i32 m0, s42, 0xc000
	ds_read_b128 v[128:131], v240
	ds_read_b128 v[132:135], v240 offset:1024
	ds_read_b128 v[136:139], v240 offset:2048
	ds_read_b128 v[140:143], v240 offset:3072
	ds_read_b128 v[144:147], v240 offset:16384
	ds_read_b128 v[148:151], v240 offset:17408
	ds_read_b128 v[152:155], v240 offset:18432
	ds_read_b128 v[156:159], v240 offset:19456
	ds_read_b128 v[160:163], v191
	ds_read_b128 v[180:183], v191 offset:1024
	ds_read_b128 v[184:187], v191 offset:2048
	ds_read_b128 v[192:195], v191 offset:3072
	ds_read_b128 v[206:209], v191 offset:4096
	ds_read_b128 v[210:213], v191 offset:5120
	ds_read_b128 v[214:217], v191 offset:6144
	ds_read_b128 v[218:221], v191 offset:7168
	global_load_lds_dwordx4 v176, s[4:5]
	s_add_i32 m0, s42, 0xe000
	s_nop 0
	global_load_lds_dwordx4 v178, s[4:5]
	s_add_i32 s56, s34, 2
	s_add_u32 s57, s4, 0x80
	s_addc_u32 s35, s5, 0
	s_add_i32 s60, 0, 0x10000
	s_cmp_eq_u32 s50, s34
	s_cselect_b32 s35, s29, s35
	s_cselect_b32 s34, s28, s57
	s_cselect_b32 s59, s31, s37
	s_cselect_b32 s58, s30, s36
	s_add_i32 s57, 0, 0x14000
	s_waitcnt vmcnt(8)
	s_waitcnt lgkmcnt(0)
	s_barrier
	s_waitcnt lgkmcnt(0)
	v_mfma_f32_16x16x32_bf16 v[124:127], v[128:131], v[160:163], v[124:127]
	v_mfma_f32_16x16x32_bf16 v[120:123], v[136:139], v[160:163], v[120:123]
	v_mfma_f32_16x16x32_bf16 v[112:115], v[128:131], v[184:187], v[112:115]
	v_mfma_f32_16x16x32_bf16 v[104:107], v[136:139], v[184:187], v[104:107]
	v_mfma_f32_16x16x32_bf16 v[96:99], v[128:131], v[206:209], v[96:99]
	v_mfma_f32_16x16x32_bf16 v[88:91], v[136:139], v[206:209], v[88:91]
	v_mfma_f32_16x16x32_bf16 v[80:83], v[128:131], v[214:217], v[80:83]
	v_mfma_f32_16x16x32_bf16 v[72:75], v[136:139], v[214:217], v[72:75]
	v_mfma_f32_16x16x32_bf16 v[124:127], v[132:135], v[180:183], v[124:127]
	v_mfma_f32_16x16x32_bf16 v[120:123], v[140:143], v[180:183], v[120:123]
	v_mfma_f32_16x16x32_bf16 v[112:115], v[132:135], v[192:195], v[112:115]
	v_mfma_f32_16x16x32_bf16 v[104:107], v[140:143], v[192:195], v[104:107]
	v_mfma_f32_16x16x32_bf16 v[96:99], v[132:135], v[210:213], v[96:99]
	v_mfma_f32_16x16x32_bf16 v[88:91], v[140:143], v[210:213], v[88:91]
	v_mfma_f32_16x16x32_bf16 v[80:83], v[132:135], v[218:221], v[80:83]
	v_mfma_f32_16x16x32_bf16 v[72:75], v[140:143], v[218:221], v[72:75]
	v_mfma_f32_16x16x32_bf16 v[116:119], v[144:147], v[160:163], v[116:119]
	v_mfma_f32_16x16x32_bf16 v[108:111], v[152:155], v[160:163], v[108:111]
	v_mfma_f32_16x16x32_bf16 v[100:103], v[144:147], v[184:187], v[100:103]
	v_mfma_f32_16x16x32_bf16 v[92:95], v[152:155], v[184:187], v[92:95]
	v_mfma_f32_16x16x32_bf16 v[84:87], v[144:147], v[206:209], v[84:87]
	v_mfma_f32_16x16x32_bf16 v[76:79], v[152:155], v[206:209], v[76:79]
	v_mfma_f32_16x16x32_bf16 v[68:71], v[144:147], v[214:217], v[68:71]
	v_mfma_f32_16x16x32_bf16 v[64:67], v[152:155], v[214:217], v[64:67]
	v_mfma_f32_16x16x32_bf16 v[116:119], v[148:151], v[180:183], v[116:119]
	v_mfma_f32_16x16x32_bf16 v[108:111], v[156:159], v[180:183], v[108:111]
	v_mfma_f32_16x16x32_bf16 v[100:103], v[148:151], v[192:195], v[100:103]
	v_mfma_f32_16x16x32_bf16 v[92:95], v[156:159], v[192:195], v[92:95]
	v_mfma_f32_16x16x32_bf16 v[84:87], v[148:151], v[210:213], v[84:87]
	v_mfma_f32_16x16x32_bf16 v[76:79], v[156:159], v[210:213], v[76:79]
	v_mfma_f32_16x16x32_bf16 v[68:71], v[148:151], v[218:221], v[68:71]
	v_mfma_f32_16x16x32_bf16 v[64:67], v[156:159], v[218:221], v[64:67]
	s_barrier
	ds_read_b128 v[160:163], v191 offset:16384
	ds_read_b128 v[180:183], v191 offset:17408
	ds_read_b128 v[184:187], v191 offset:18432
	ds_read_b128 v[192:195], v191 offset:19456
	ds_read_b128 v[206:209], v191 offset:20480
	ds_read_b128 v[210:213], v191 offset:21504
	ds_read_b128 v[214:217], v191 offset:22528
	ds_read_b128 v[218:221], v191 offset:23552
	s_add_i32 s60, s60, s41
	s_mov_b32 m0, s60
	s_add_i32 s57, s57, s41
	global_load_lds_dwordx4 v168, s[58:59]
	s_add_i32 m0, s60, 0x2000
	s_nop 0
	global_load_lds_dwordx4 v174, s[58:59]
	s_add_u32 s58, s58, s16
	s_addc_u32 s59, s59, 0
	s_mov_b32 m0, s57
	s_nop 0
	global_load_lds_dwordx4 v168, s[58:59]
	s_add_i32 m0, s57, 0x2000
	s_nop 0
	global_load_lds_dwordx4 v174, s[58:59]
	s_mov_b32 m0, s42
	s_nop 0
	global_load_lds_dwordx4 v168, s[34:35]
	s_mov_b32 m0, s43
	s_nop 0
	global_load_lds_dwordx4 v174, s[34:35]
	s_waitcnt vmcnt(8)
	s_waitcnt lgkmcnt(0)
	s_barrier
	s_waitcnt lgkmcnt(0)
	v_mfma_f32_16x16x32_bf16 v[60:63], v[128:131], v[160:163], v[60:63]
	v_mfma_f32_16x16x32_bf16 v[56:59], v[136:139], v[160:163], v[56:59]
	v_mfma_f32_16x16x32_bf16 v[48:51], v[128:131], v[184:187], v[48:51]
	v_mfma_f32_16x16x32_bf16 v[40:43], v[136:139], v[184:187], v[40:43]
	v_mfma_f32_16x16x32_bf16 v[32:35], v[128:131], v[206:209], v[32:35]
	v_mfma_f32_16x16x32_bf16 v[24:27], v[136:139], v[206:209], v[24:27]
	v_mfma_f32_16x16x32_bf16 v[16:19], v[128:131], v[214:217], v[16:19]
	v_mfma_f32_16x16x32_bf16 v[8:11], v[136:139], v[214:217], v[8:11]
	v_mfma_f32_16x16x32_bf16 v[60:63], v[132:135], v[180:183], v[60:63]
	v_mfma_f32_16x16x32_bf16 v[56:59], v[140:143], v[180:183], v[56:59]
	v_mfma_f32_16x16x32_bf16 v[48:51], v[132:135], v[192:195], v[48:51]
	v_mfma_f32_16x16x32_bf16 v[40:43], v[140:143], v[192:195], v[40:43]
	v_mfma_f32_16x16x32_bf16 v[32:35], v[132:135], v[210:213], v[32:35]
	v_mfma_f32_16x16x32_bf16 v[24:27], v[140:143], v[210:213], v[24:27]
	v_mfma_f32_16x16x32_bf16 v[16:19], v[132:135], v[218:221], v[16:19]
	v_mfma_f32_16x16x32_bf16 v[8:11], v[140:143], v[218:221], v[8:11]
	v_mfma_f32_16x16x32_bf16 v[52:55], v[144:147], v[160:163], v[52:55]
	v_mfma_f32_16x16x32_bf16 v[44:47], v[152:155], v[160:163], v[44:47]
	v_mfma_f32_16x16x32_bf16 v[36:39], v[144:147], v[184:187], v[36:39]
	v_mfma_f32_16x16x32_bf16 v[28:31], v[152:155], v[184:187], v[28:31]
	v_mfma_f32_16x16x32_bf16 v[20:23], v[144:147], v[206:209], v[20:23]
	v_mfma_f32_16x16x32_bf16 v[12:15], v[152:155], v[206:209], v[12:15]
	v_mfma_f32_16x16x32_bf16 v[4:7], v[144:147], v[214:217], v[4:7]
	v_mfma_f32_16x16x32_bf16 v[0:3], v[152:155], v[214:217], v[0:3]
	v_mfma_f32_16x16x32_bf16 v[52:55], v[148:151], v[180:183], v[52:55]
	v_mfma_f32_16x16x32_bf16 v[44:47], v[156:159], v[180:183], v[44:47]
	v_mfma_f32_16x16x32_bf16 v[36:39], v[148:151], v[192:195], v[36:39]
	v_mfma_f32_16x16x32_bf16 v[28:31], v[156:159], v[192:195], v[28:31]
	v_mfma_f32_16x16x32_bf16 v[20:23], v[148:151], v[210:213], v[20:23]
	v_mfma_f32_16x16x32_bf16 v[12:15], v[156:159], v[210:213], v[12:15]
	v_mfma_f32_16x16x32_bf16 v[4:7], v[148:151], v[218:221], v[4:7]
	v_mfma_f32_16x16x32_bf16 v[0:3], v[156:159], v[218:221], v[0:3]
	s_barrier
; #define PG8_STAGE(bufoff, gbase, voff) do { _Pragma("unroll") for (int _i = 0; _i < 2; ++_i) \
;         __builtin_amdgcn_global_load_lds((const unsigned*)((const char*)(gbase) + (voff)[_i]), (LAS unsigned*)(lds + (bufoff) + ldsw + _i * 8192), 16, 0, 0); } while (0)
; #define PG8_LDA(dst, b, h) do { _Pragma("unroll") for (int m = 0; m < 4; ++m) _Pragma("unroll") for (int k = 0; k < 2; ++k) dst[m][k] = *(const LAS bf16x8*)(lds + PG8_SA(b, h) + aoff + m * 2048 + k * 1024); } while (0)
; #define PG8_LDB(dst, b, h) do { _Pragma("unroll") for (int n = 0; n < 2; ++n) _Pragma("unroll") for (int k = 0; k < 2; ++k) dst[n][k] = *(const LAS bf16x8*)(lds + PG8_SB(b, h) + boff + n * 2048 + k * 1024); } while (0)
; #define PG8_MMA(ai, bj, At, Bt) do { __builtin_amdgcn_s_setprio(1); _Pragma("unroll") for (int m = 0; m < 4; ++m) _Pragma("unroll") for (int n = 0; n < 2; ++n) _Pragma("unroll") for (int k = 0; k < 2; ++k) \
;         acc[ai][bj][m][n] = __builtin_amdgcn_mfma_f32_16x16x32_bf16(Bt[n][k], At[m][k], acc[ai][bj][m][n], 0, 0, 0); __builtin_amdgcn_s_setprio(0); } while (0)
; #define PG8_WAIT_V(n) asm volatile("s_waitcnt vmcnt(" #n ")" ::: "memory")
; #define PG8_WAIT_L(n) asm volatile("s_waitcnt lgkmcnt(" #n ")" ::: "memory")
; #define PG8_BAR __builtin_amdgcn_s_barrier()
; #define PG8_SCHED __builtin_amdgcn_sched_barrier(0)
; template <class Epi>
; __device__ __forceinline__ void gemm_phase(LAS unsigned char* lds, const Gemm g, const StaticOrder& S, const Epi& E) {
;     ...
;             PG8_LDB(B0, 1, 0); PG8_LDB(B1, 1, 1); PG8_SCHED; PG8_LDA(At, 1, 0); PG8_STAGE(PG8_SA(0, 1), a2 + hA, voffA);
;             PG8_WAIT_V(8); PG8_WAIT_L(0); PG8_BAR; PG8_MMA(0, 0, At, B0); PG8_MMA(0, 1, At, B1); PG8_BAR; PG8_SCHED;
;             PG8_LDA(At, 1, 1); PG8_STAGE(PG8_SB(1, 0), b3, voffB); PG8_STAGE(PG8_SB(1, 1), b3 + hB, voffB); PG8_STAGE(PG8_SA(1, 0), a3, voffA);
;             PG8_WAIT_V(8); PG8_WAIT_L(0); PG8_BAR; PG8_MMA(1, 0, At, B0); PG8_MMA(1, 1, At, B1); PG8_BAR; PG8_SCHED;
;         }
;         if (wr == 0) PG8_BAR;
	ds_read_b128 v[128:131], v240 offset:32768
	ds_read_b128 v[132:135], v240 offset:33792
	ds_read_b128 v[136:139], v240 offset:34816
	ds_read_b128 v[140:143], v240 offset:35840
	ds_read_b128 v[144:147], v240 offset:49152
	ds_read_b128 v[148:151], v240 offset:50176
	ds_read_b128 v[152:155], v240 offset:51200
	ds_read_b128 v[156:159], v240 offset:52224
	ds_read_b128 v[160:163], v191 offset:32768
	ds_read_b128 v[180:183], v191 offset:33792
	ds_read_b128 v[184:187], v191 offset:34816
	ds_read_b128 v[192:195], v191 offset:35840
	ds_read_b128 v[206:209], v191 offset:36864
	ds_read_b128 v[210:213], v191 offset:37888
	ds_read_b128 v[214:217], v191 offset:38912
	ds_read_b128 v[218:221], v191 offset:39936
	s_add_u32 s34, s34, s16
	s_addc_u32 s35, s35, 0
	s_mov_b32 m0, s44
	s_add_i32 s60, 0, 0x18000
	global_load_lds_dwordx4 v168, s[34:35]
	s_mov_b32 m0, s45
	s_nop 0
	global_load_lds_dwordx4 v174, s[34:35]
	s_waitcnt vmcnt(8)
	s_waitcnt lgkmcnt(0)
	s_barrier
	s_waitcnt lgkmcnt(0)
	v_mfma_f32_16x16x32_bf16 v[124:127], v[128:131], v[160:163], v[124:127]
	v_mfma_f32_16x16x32_bf16 v[120:123], v[136:139], v[160:163], v[120:123]
	v_mfma_f32_16x16x32_bf16 v[112:115], v[128:131], v[184:187], v[112:115]
	v_mfma_f32_16x16x32_bf16 v[104:107], v[136:139], v[184:187], v[104:107]
	v_mfma_f32_16x16x32_bf16 v[96:99], v[128:131], v[206:209], v[96:99]
	v_mfma_f32_16x16x32_bf16 v[88:91], v[136:139], v[206:209], v[88:91]
	v_mfma_f32_16x16x32_bf16 v[80:83], v[128:131], v[214:217], v[80:83]
	v_mfma_f32_16x16x32_bf16 v[72:75], v[136:139], v[214:217], v[72:75]
	v_mfma_f32_16x16x32_bf16 v[124:127], v[132:135], v[180:183], v[124:127]
	v_mfma_f32_16x16x32_bf16 v[120:123], v[140:143], v[180:183], v[120:123]
	v_mfma_f32_16x16x32_bf16 v[112:115], v[132:135], v[192:195], v[112:115]
	v_mfma_f32_16x16x32_bf16 v[104:107], v[140:143], v[192:195], v[104:107]
	v_mfma_f32_16x16x32_bf16 v[96:99], v[132:135], v[210:213], v[96:99]
	v_mfma_f32_16x16x32_bf16 v[88:91], v[140:143], v[210:213], v[88:91]
	v_mfma_f32_16x16x32_bf16 v[80:83], v[132:135], v[218:221], v[80:83]
	v_mfma_f32_16x16x32_bf16 v[72:75], v[140:143], v[218:221], v[72:75]
	v_mfma_f32_16x16x32_bf16 v[116:119], v[144:147], v[160:163], v[116:119]
	v_mfma_f32_16x16x32_bf16 v[108:111], v[152:155], v[160:163], v[108:111]
	v_mfma_f32_16x16x32_bf16 v[100:103], v[144:147], v[184:187], v[100:103]
	v_mfma_f32_16x16x32_bf16 v[92:95], v[152:155], v[184:187], v[92:95]
	v_mfma_f32_16x16x32_bf16 v[84:87], v[144:147], v[206:209], v[84:87]
	v_mfma_f32_16x16x32_bf16 v[76:79], v[152:155], v[206:209], v[76:79]
	v_mfma_f32_16x16x32_bf16 v[68:71], v[144:147], v[214:217], v[68:71]
	v_mfma_f32_16x16x32_bf16 v[64:67], v[152:155], v[214:217], v[64:67]
	v_mfma_f32_16x16x32_bf16 v[116:119], v[148:151], v[180:183], v[116:119]
	v_mfma_f32_16x16x32_bf16 v[108:111], v[156:159], v[180:183], v[108:111]
	v_mfma_f32_16x16x32_bf16 v[100:103], v[148:151], v[192:195], v[100:103]
	v_mfma_f32_16x16x32_bf16 v[92:95], v[156:159], v[192:195], v[92:95]
	v_mfma_f32_16x16x32_bf16 v[84:87], v[148:151], v[210:213], v[84:87]
	v_mfma_f32_16x16x32_bf16 v[76:79], v[156:159], v[210:213], v[76:79]
	v_mfma_f32_16x16x32_bf16 v[68:71], v[148:151], v[218:221], v[68:71]
	v_mfma_f32_16x16x32_bf16 v[64:67], v[156:159], v[218:221], v[64:67]
	s_barrier
	ds_read_b128 v[160:163], v191 offset:49152
	ds_read_b128 v[180:183], v191 offset:50176
	ds_read_b128 v[184:187], v191 offset:51200
	ds_read_b128 v[192:195], v191 offset:52224
	ds_read_b128 v[206:209], v191 offset:53248
	ds_read_b128 v[210:213], v191 offset:54272
	ds_read_b128 v[214:217], v191 offset:55296
	ds_read_b128 v[218:221], v191 offset:56320
	s_add_i32 s60, s60, s41
	s_add_i32 m0, s60, 0x4000
	s_nop 0
	global_load_lds_dwordx4 v241, s[58:59]
	s_add_i32 m0, s60, 0x6000
	s_nop 0
	global_load_lds_dwordx4 v242, s[58:59]
	s_sub_u32 s58, s58, s16
	s_subb_u32 s59, s59, 0
	s_mov_b32 m0, s60
	s_nop 0
	global_load_lds_dwordx4 v241, s[58:59]
	s_add_i32 m0, s60, 0x2000
	s_nop 0
	global_load_lds_dwordx4 v242, s[58:59]
	s_sub_u32 s34, s34, s16
	s_subb_u32 s35, s35, 0
	s_mov_b32 m0, s48
	s_nop 0
	global_load_lds_dwordx4 v241, s[34:35]
	s_mov_b32 m0, s49
	s_nop 0
	global_load_lds_dwordx4 v242, s[34:35]
	s_waitcnt vmcnt(8)
	s_waitcnt lgkmcnt(0)
	s_barrier
	s_waitcnt lgkmcnt(0)
	v_mfma_f32_16x16x32_bf16 v[60:63], v[128:131], v[160:163], v[60:63]
	v_mfma_f32_16x16x32_bf16 v[56:59], v[136:139], v[160:163], v[56:59]
	v_mfma_f32_16x16x32_bf16 v[48:51], v[128:131], v[184:187], v[48:51]
	v_mfma_f32_16x16x32_bf16 v[40:43], v[136:139], v[184:187], v[40:43]
	v_mfma_f32_16x16x32_bf16 v[32:35], v[128:131], v[206:209], v[32:35]
	v_mfma_f32_16x16x32_bf16 v[24:27], v[136:139], v[206:209], v[24:27]
	v_mfma_f32_16x16x32_bf16 v[16:19], v[128:131], v[214:217], v[16:19]
	v_mfma_f32_16x16x32_bf16 v[8:11], v[136:139], v[214:217], v[8:11]
	v_mfma_f32_16x16x32_bf16 v[60:63], v[132:135], v[180:183], v[60:63]
	v_mfma_f32_16x16x32_bf16 v[56:59], v[140:143], v[180:183], v[56:59]
	v_mfma_f32_16x16x32_bf16 v[48:51], v[132:135], v[192:195], v[48:51]
	v_mfma_f32_16x16x32_bf16 v[40:43], v[140:143], v[192:195], v[40:43]
	v_mfma_f32_16x16x32_bf16 v[32:35], v[132:135], v[210:213], v[32:35]
	v_mfma_f32_16x16x32_bf16 v[24:27], v[140:143], v[210:213], v[24:27]
	v_mfma_f32_16x16x32_bf16 v[16:19], v[132:135], v[218:221], v[16:19]
	v_mfma_f32_16x16x32_bf16 v[8:11], v[140:143], v[218:221], v[8:11]
	v_mfma_f32_16x16x32_bf16 v[52:55], v[144:147], v[160:163], v[52:55]
	v_mfma_f32_16x16x32_bf16 v[44:47], v[152:155], v[160:163], v[44:47]
	v_mfma_f32_16x16x32_bf16 v[36:39], v[144:147], v[184:187], v[36:39]
	v_mfma_f32_16x16x32_bf16 v[28:31], v[152:155], v[184:187], v[28:31]
	v_mfma_f32_16x16x32_bf16 v[20:23], v[144:147], v[206:209], v[20:23]
	v_mfma_f32_16x16x32_bf16 v[12:15], v[152:155], v[206:209], v[12:15]
	v_mfma_f32_16x16x32_bf16 v[4:7], v[144:147], v[214:217], v[4:7]
	v_mfma_f32_16x16x32_bf16 v[0:3], v[152:155], v[214:217], v[0:3]
	v_mfma_f32_16x16x32_bf16 v[52:55], v[148:151], v[180:183], v[52:55]
	v_mfma_f32_16x16x32_bf16 v[44:47], v[156:159], v[180:183], v[44:47]
	v_mfma_f32_16x16x32_bf16 v[36:39], v[148:151], v[192:195], v[36:39]
	v_mfma_f32_16x16x32_bf16 v[28:31], v[156:159], v[192:195], v[28:31]
	v_mfma_f32_16x16x32_bf16 v[20:23], v[148:151], v[210:213], v[20:23]
	v_mfma_f32_16x16x32_bf16 v[12:15], v[156:159], v[210:213], v[12:15]
	v_mfma_f32_16x16x32_bf16 v[4:7], v[148:151], v[218:221], v[4:7]
	v_mfma_f32_16x16x32_bf16 v[0:3], v[156:159], v[218:221], v[0:3]
	s_barrier
	s_add_u32 s4, s4, 0x100
	s_addc_u32 s5, s5, 0
	s_add_u32 s36, s36, 0x100
	s_addc_u32 s37, s37, 0
	s_cmp_ge_u32 s56, s47
	s_mov_b32 s34, s56
	s_cbranch_scc0 .LBB0_342
	s_and_b64 vcc, exec, s[24:25]
	s_cbranch_vccz .LBB0_345
	s_barrier

; #define PG8_WAIT_V(n) asm volatile("s_waitcnt vmcnt(" #n ")" ::: "memory")
; #define PG8_BAR __builtin_amdgcn_s_barrier()
; template <class Epi>
; __device__ __forceinline__ void gemm_phase(LAS unsigned char* lds, const Gemm g, const StaticOrder& S, const Epi& E) {
;     ...
;     PG8_WAIT_V(0);
;     PG8_BAR;
.LBB0_396:
	s_setprio 0
	s_waitcnt vmcnt(0)
	s_barrier

; __device__ __forceinline__ int tid_fresh() { int t = threadIdx.x; asm volatile("" : "+v"(t)); return t; }
; #define PG8_STAGE(bufoff, gbase, voff) do { _Pragma("unroll") for (int _i = 0; _i < 2; ++_i) \
;         __builtin_amdgcn_global_load_lds((const unsigned*)((const char*)(gbase) + (voff)[_i]), (LAS unsigned*)(lds + (bufoff) + ldsw + _i * 8192), 16, 0, 0); } while (0)
; #define PG8_WAIT_V(n) asm volatile("s_waitcnt vmcnt(" #n ")" ::: "memory")
; template <class Epi>
; __device__ __forceinline__ void gemm_phase(LAS unsigned char* lds, const Gemm g, const StaticOrder& S, const Epi& E) {
;     const int tid = tid_fresh(), wid = __builtin_amdgcn_readfirstlane(tid >> 6), lane = tid & 63, wr = wid >> 2, wc = wid & 3, fr = lane & 15, fq = lane >> 4;
;     const int K = g.K, nt = K / BK, lda = g.lda;
;     unsigned voffA[2], voffB[2];
; #pragma unroll
;     for (int i = 0; i < 2; ++i) { int R, C; stage_rc(tid * 16 + i * 8192, R, C); const int Rb = Epi::PERM ? ((R & ~31) + perm32(R & 31)) : R;
;         voffA[i] = (unsigned)(R * lda + C) * 2u; voffB[i] = (unsigned)(Rb * K + C) * 2u; }
;     const size_t kstep = (size_t)(BK * 2);
;     const size_t hA = (size_t)HALF * lda * 2, hB = (size_t)HALF * K * 2;
;     const size_t tA = 2 * hA, tB = 2 * hB;
;     const unsigned ldsw = (unsigned)wid * 1024u;
;     const int aoff = lds_byte(wr * 64 + fr, fq * 8), boff = lds_byte(wc * 32 + fr, fq * 8);
;     ...
;     Unit cur, nxt; int ui = 0;
;     if (!S.next(0, cur)) return;
;     f32x4 acc[2][2][4][2];
; #pragma unroll
;     for (int a = 0; a < 2; ++a)
; #pragma unroll
;         for (int b = 0; b < 2; ++b)
; #pragma unroll
;             for (int m = 0; m < 4; ++m)
; #pragma unroll
;                 for (int n = 0; n < 2; ++n) acc[a][b][m][n] = (f32x4){0.f, 0.f, 0.f, 0.f};
;     bf16x8 At[4][2], B0[2][2], B1[2][2];
;     const char* cA = (const char*)g.A + (size_t)cur.pm * tA + (g.agrp ? (size_t)(cur.pn >> 1) * 1024 : 0);
;     const char* cB = (const char*)g.Bt + (size_t)cur.pn * tB;
;     PG8_STAGE(PG8_SB(0, 0), cB, voffB); PG8_STAGE(PG8_SB(0, 1), cB + hB, voffB); PG8_STAGE(PG8_SA(0, 0), cA, voffA); PG8_STAGE(PG8_SA(0, 1), cA + hA, voffA);
;     if (wr == 1) PG8_BAR;
;     PG8_WAIT_V(2); PG8_BAR;
;     PG8_STAGE(PG8_SB(1, 0), cB + kstep, voffB); PG8_STAGE(PG8_SA(1, 0), cA + kstep, voffA); PG8_STAGE(PG8_SB(1, 1), cB + hB + kstep, voffB);
;     PG8_WAIT_V(6); PG8_BAR;
.LBB0_421:
	s_and_b32 s53, s6, 3
	s_lshr_b32 s54, s20, 6
	s_lshl_b32 s6, s7, 13
	s_lshl_b32 s25, s53, 12
	s_add_u32 s20, s74, 0x1b784000
	s_addc_u32 s21, s75, 0
	s_add_u32 s22, s74, 0x4000
	s_addc_u32 s23, s75, 0
	s_add_i32 m0, s49, 0x18000
	v_lshl_add_u64 v[8:9], v[8:9], 0, s[80:81]
	s_waitcnt vmcnt(2)
	s_barrier
	global_load_lds_dwordx4 v[8:9], off
	v_lshl_add_u64 v[4:5], v[4:5], 0, s[80:81]
	s_add_i32 m0, s49, 0x1a000
	s_add_i32 s55, s49, 0x8000
	global_load_lds_dwordx4 v[4:5], off
	v_lshl_add_u64 v[4:5], v[6:7], 0, s[80:81]
	s_mov_b32 m0, s55
	s_add_i32 s56, s49, 0xa000
	global_load_lds_dwordx4 v[4:5], off
	v_lshl_add_u64 v[4:5], v[10:11], 0, s[80:81]
	s_mov_b32 m0, s56
	v_lshl_add_u64 v[2:3], v[2:3], 0, s[80:81]
	global_load_lds_dwordx4 v[4:5], off
	s_add_i32 m0, s49, 0x1c000
	v_lshl_add_u64 v[0:1], v[0:1], 0, s[80:81]
	global_load_lds_dwordx4 v[2:3], off
	s_add_i32 m0, s49, 0x1e000
	s_add_i32 s57, s54, -2
	global_load_lds_dwordx4 v[0:1], off
	v_bfe_u32 v0, v12, 4, 2
	v_and_b32_e32 v1, 15, v12
	v_lshlrev_b32_e32 v3, 4, v0
	v_lshl_or_b32 v206, s7, 6, v1
	s_cmp_eq_u32 s7, 1
	s_cbranch_scc0 .Lprio_done_2
	s_setprio 1
.Lprio_done_2:
	v_lshl_or_b32 v1, v1, 6, v3
	v_lshlrev_b32_e32 v3, 2, v12
	v_and_b32_e32 v3, 32, v3
	s_cmpk_lt_u32 s24, 0x100
	v_bitop3_b32 v207, v1, s25, v3 bitop3:0xde
	v_add_u32_e32 v240, 0x10000, v207
	v_add_u32_e32 v241, 0x80, v168
	v_add_u32_e32 v242, 0x80, v164
	v_add_u32_e32 v243, 0x80, v160
	v_add_u32_e32 v244, 0x80, v162
	s_cselect_b64 s[24:25], -1, 0
	s_ashr_i32 s59, s44, 31
	s_ashr_i32 s60, s45, 31
	s_lshr_b32 s61, s42, 5
	s_and_b64 s[4:5], s[4:5], exec
	s_cselect_b32 s63, 2, 3
	s_cselect_b32 s62, 4, 8
	s_lshl_b32 s64, s17, s63
	v_bitop3_b32 v4, v1, s6, v3 bitop3:0xde
	v_cvt_f32_u32_e32 v1, s64
	v_lshlrev_b32_e32 v2, 3, v0
	v_cmp_eq_u32_e64 s[4:5], 0, v0
	v_lshlrev_b32_e32 v0, 5, v0
	v_rcp_iflag_f32_e32 v3, v1
	v_mov_b32_e32 v1, v169
	v_lshl_add_u64 v[174:175], s[0:1], 0, v[0:1]
	v_lshlrev_b32_e32 v0, 15, v13
	v_mul_f32_e32 v3, 0x4f7ffffe, v3
	v_cvt_u32_f32_e32 v3, v3
	v_and_b32_e32 v0, 0xffff0000, v0
	v_lshl_add_u32 v0, v14, 12, v0
	v_and_b32_e32 v1, 1, v13
	v_lshl_or_b32 v0, v1, 6, v0
	s_cmp_lg_u64 s[0:1], 0
	v_lshl_add_u32 v176, v15, 1, v0
	v_lshlrev_b32_e32 v0, 15, v16
	s_cselect_b64 s[26:27], -1, 0
	s_sub_i32 s0, 0, s64
	v_readfirstlane_b32 s1, v3
	v_and_b32_e32 v0, 0xffff0000, v0
	s_waitcnt vmcnt(6)
	s_mul_i32 s0, s0, s1
	v_lshl_add_u32 v0, v17, 12, v0
	v_and_b32_e32 v1, 1, v16
	s_mul_hi_u32 s0, s1, s0
	v_lshl_or_b32 v0, v1, 6, v0
	s_mov_b32 s58, 0
	s_mov_b32 s17, s3
	v_lshl_or_b32 v208, s53, 5, v2
	s_add_i32 s65, s1, s0
	v_mov_b32_e32 v177, v169
	v_lshl_add_u32 v178, v18, 1, v0
	v_mov_b32_e32 v179, v169
	v_add_u32_e32 v209, 0, v4
	s_barrier
	s_branch .LBB0_424

; #define PG8_STAGE(bufoff, gbase, voff) do { _Pragma("unroll") for (int _i = 0; _i < 2; ++_i) \
;         __builtin_amdgcn_global_load_lds((const unsigned*)((const char*)(gbase) + (voff)[_i]), (LAS unsigned*)(lds + (bufoff) + ldsw + _i * 8192), 16, 0, 0); } while (0)
; #define PG8_LDA(dst, b, h) do { _Pragma("unroll") for (int m = 0; m < 4; ++m) _Pragma("unroll") for (int k = 0; k < 2; ++k) dst[m][k] = *(const LAS bf16x8*)(lds + PG8_SA(b, h) + aoff + m * 2048 + k * 1024); } while (0)
; #define PG8_LDB(dst, b, h) do { _Pragma("unroll") for (int n = 0; n < 2; ++n) _Pragma("unroll") for (int k = 0; k < 2; ++k) dst[n][k] = *(const LAS bf16x8*)(lds + PG8_SB(b, h) + boff + n * 2048 + k * 1024); } while (0)
; #define PG8_MMA(ai, bj, At, Bt) do { __builtin_amdgcn_s_setprio(1); _Pragma("unroll") for (int m = 0; m < 4; ++m) _Pragma("unroll") for (int n = 0; n < 2; ++n) _Pragma("unroll") for (int k = 0; k < 2; ++k) \
;         acc[ai][bj][m][n] = __builtin_amdgcn_mfma_f32_16x16x32_bf16(Bt[n][k], At[m][k], acc[ai][bj][m][n], 0, 0, 0); __builtin_amdgcn_s_setprio(0); } while (0)
; #define PG8_WAIT_V(n) asm volatile("s_waitcnt vmcnt(" #n ")" ::: "memory")
; #define PG8_WAIT_L(n) asm volatile("s_waitcnt lgkmcnt(" #n ")" ::: "memory")
; #define PG8_BAR __builtin_amdgcn_s_barrier()
; #define PG8_SCHED __builtin_amdgcn_sched_barrier(0)
; template <class Epi>
; __device__ __forceinline__ void gemm_phase(LAS unsigned char* lds, const Gemm g, const StaticOrder& S, const Epi& E) {
;     ...
;             PG8_LDB(B0, 0, 0); PG8_LDB(B1, 0, 1); PG8_SCHED; PG8_LDA(At, 0, 0); PG8_STAGE(PG8_SA(1, 1), a1 + hA, voffA);
;             PG8_WAIT_V(8); PG8_WAIT_L(0); PG8_BAR; PG8_MMA(0, 0, At, B0); PG8_MMA(0, 1, At, B1); PG8_BAR; PG8_SCHED;
;             PG8_LDA(At, 0, 1); PG8_STAGE(PG8_SB(0, 0), b2, voffB); PG8_STAGE(PG8_SB(0, 1), b2 + hB, voffB); PG8_STAGE(PG8_SA(0, 0), a2, voffA);
;             PG8_WAIT_V(8); PG8_WAIT_L(0); PG8_BAR; PG8_MMA(1, 0, At, B0); PG8_MMA(1, 1, At, B1); PG8_BAR; PG8_SCHED;
.LBB0_431:
	s_add_i32 m0, s49, 0xc000
	ds_read_b128 v[128:131], v240
	ds_read_b128 v[132:135], v240 offset:1024
	ds_read_b128 v[136:139], v240 offset:2048
	ds_read_b128 v[140:143], v240 offset:3072
	ds_read_b128 v[144:147], v240 offset:16384
	ds_read_b128 v[148:151], v240 offset:17408
	ds_read_b128 v[152:155], v240 offset:18432
	ds_read_b128 v[156:159], v240 offset:19456
	ds_read_b128 v[180:183], v209
	ds_read_b128 v[184:187], v209 offset:1024
	ds_read_b128 v[188:191], v209 offset:2048
	ds_read_b128 v[192:195], v209 offset:3072
	ds_read_b128 v[210:213], v209 offset:4096
	ds_read_b128 v[214:217], v209 offset:5120
	ds_read_b128 v[218:221], v209 offset:6144
	ds_read_b128 v[222:225], v209 offset:7168
	global_load_lds_dwordx4 v176, s[0:1]
	s_add_i32 m0, s49, 0xe000
	s_nop 0
	global_load_lds_dwordx4 v178, s[0:1]
	s_add_i32 s40, s37, 2
	s_add_u32 s38, s0, 0xfff80080
	s_addc_u32 s39, s1, -1
	s_add_i32 s41, 0, 0x10000
	s_cmp_eq_u32 s57, s37
	s_cselect_b32 s39, s31, s39
	s_cselect_b32 s38, s30, s38
	s_cselect_b32 s69, s35, s33
	s_cselect_b32 s68, s34, s29
	s_add_i32 s37, 0, 0x14000
	s_waitcnt vmcnt(8)
	s_waitcnt lgkmcnt(0)
	s_barrier
	s_waitcnt lgkmcnt(0)
	v_mfma_f32_16x16x32_bf16 v[124:127], v[128:131], v[180:183], v[124:127]
	v_mfma_f32_16x16x32_bf16 v[120:123], v[136:139], v[180:183], v[120:123]
	v_mfma_f32_16x16x32_bf16 v[108:111], v[128:131], v[188:191], v[108:111]
	v_mfma_f32_16x16x32_bf16 v[104:107], v[136:139], v[188:191], v[104:107]
	v_mfma_f32_16x16x32_bf16 v[92:95], v[128:131], v[210:213], v[92:95]
	v_mfma_f32_16x16x32_bf16 v[88:91], v[136:139], v[210:213], v[88:91]
	v_mfma_f32_16x16x32_bf16 v[76:79], v[128:131], v[218:221], v[76:79]
	v_mfma_f32_16x16x32_bf16 v[72:75], v[136:139], v[218:221], v[72:75]
	v_mfma_f32_16x16x32_bf16 v[124:127], v[132:135], v[184:187], v[124:127]
	v_mfma_f32_16x16x32_bf16 v[120:123], v[140:143], v[184:187], v[120:123]
	v_mfma_f32_16x16x32_bf16 v[108:111], v[132:135], v[192:195], v[108:111]
	v_mfma_f32_16x16x32_bf16 v[104:107], v[140:143], v[192:195], v[104:107]
	v_mfma_f32_16x16x32_bf16 v[92:95], v[132:135], v[214:217], v[92:95]
	v_mfma_f32_16x16x32_bf16 v[88:91], v[140:143], v[214:217], v[88:91]
	v_mfma_f32_16x16x32_bf16 v[76:79], v[132:135], v[222:225], v[76:79]
	v_mfma_f32_16x16x32_bf16 v[72:75], v[140:143], v[222:225], v[72:75]
	v_mfma_f32_16x16x32_bf16 v[116:119], v[144:147], v[180:183], v[116:119]
	v_mfma_f32_16x16x32_bf16 v[112:115], v[152:155], v[180:183], v[112:115]
	v_mfma_f32_16x16x32_bf16 v[100:103], v[144:147], v[188:191], v[100:103]
	v_mfma_f32_16x16x32_bf16 v[96:99], v[152:155], v[188:191], v[96:99]
	v_mfma_f32_16x16x32_bf16 v[84:87], v[144:147], v[210:213], v[84:87]
	v_mfma_f32_16x16x32_bf16 v[80:83], v[152:155], v[210:213], v[80:83]
	v_mfma_f32_16x16x32_bf16 v[68:71], v[144:147], v[218:221], v[68:71]
	v_mfma_f32_16x16x32_bf16 v[64:67], v[152:155], v[218:221], v[64:67]
	v_mfma_f32_16x16x32_bf16 v[116:119], v[148:151], v[184:187], v[116:119]
	v_mfma_f32_16x16x32_bf16 v[112:115], v[156:159], v[184:187], v[112:115]
	v_mfma_f32_16x16x32_bf16 v[100:103], v[148:151], v[192:195], v[100:103]
	v_mfma_f32_16x16x32_bf16 v[96:99], v[156:159], v[192:195], v[96:99]
	v_mfma_f32_16x16x32_bf16 v[84:87], v[148:151], v[214:217], v[84:87]
	v_mfma_f32_16x16x32_bf16 v[80:83], v[156:159], v[214:217], v[80:83]
	v_mfma_f32_16x16x32_bf16 v[68:71], v[148:151], v[222:225], v[68:71]
	v_mfma_f32_16x16x32_bf16 v[64:67], v[156:159], v[222:225], v[64:67]
	s_barrier
	ds_read_b128 v[180:183], v209 offset:16384
	ds_read_b128 v[184:187], v209 offset:17408
	ds_read_b128 v[188:191], v209 offset:18432
	ds_read_b128 v[192:195], v209 offset:19456
	ds_read_b128 v[210:213], v209 offset:20480
	ds_read_b128 v[214:217], v209 offset:21504
	ds_read_b128 v[218:221], v209 offset:22528
	ds_read_b128 v[222:225], v209 offset:23552
	s_add_i32 s41, s41, s48
	s_mov_b32 m0, s41
	s_add_i32 s37, s37, s48
	global_load_lds_dwordx4 v168, s[68:69]
	s_add_i32 m0, s41, 0x2000
	s_nop 0
	global_load_lds_dwordx4 v164, s[68:69]
	s_add_u32 s68, s68, s46
	s_addc_u32 s69, s69, 0
	s_mov_b32 m0, s37
	s_nop 0
	global_load_lds_dwordx4 v168, s[68:69]
	s_add_i32 m0, s37, 0x2000
	s_nop 0
	global_load_lds_dwordx4 v164, s[68:69]
	s_mov_b32 m0, s49
	s_nop 0
	global_load_lds_dwordx4 v160, s[38:39]
	s_mov_b32 m0, s50
	s_nop 0
	global_load_lds_dwordx4 v162, s[38:39]
	s_waitcnt vmcnt(8)
	s_waitcnt lgkmcnt(0)
	s_barrier
	s_waitcnt lgkmcnt(0)
	v_mfma_f32_16x16x32_bf16 v[60:63], v[128:131], v[180:183], v[60:63]
	v_mfma_f32_16x16x32_bf16 v[56:59], v[136:139], v[180:183], v[56:59]
	v_mfma_f32_16x16x32_bf16 v[44:47], v[128:131], v[188:191], v[44:47]
	v_mfma_f32_16x16x32_bf16 v[40:43], v[136:139], v[188:191], v[40:43]
	v_mfma_f32_16x16x32_bf16 v[28:31], v[128:131], v[210:213], v[28:31]
	v_mfma_f32_16x16x32_bf16 v[24:27], v[136:139], v[210:213], v[24:27]
	v_mfma_f32_16x16x32_bf16 v[12:15], v[128:131], v[218:221], v[12:15]
	v_mfma_f32_16x16x32_bf16 v[8:11], v[136:139], v[218:221], v[8:11]
	v_mfma_f32_16x16x32_bf16 v[60:63], v[132:135], v[184:187], v[60:63]
	v_mfma_f32_16x16x32_bf16 v[56:59], v[140:143], v[184:187], v[56:59]
	v_mfma_f32_16x16x32_bf16 v[44:47], v[132:135], v[192:195], v[44:47]
	v_mfma_f32_16x16x32_bf16 v[40:43], v[140:143], v[192:195], v[40:43]
	v_mfma_f32_16x16x32_bf16 v[28:31], v[132:135], v[214:217], v[28:31]
	v_mfma_f32_16x16x32_bf16 v[24:27], v[140:143], v[214:217], v[24:27]
	v_mfma_f32_16x16x32_bf16 v[12:15], v[132:135], v[222:225], v[12:15]
	v_mfma_f32_16x16x32_bf16 v[8:11], v[140:143], v[222:225], v[8:11]
	v_mfma_f32_16x16x32_bf16 v[52:55], v[144:147], v[180:183], v[52:55]
	v_mfma_f32_16x16x32_bf16 v[48:51], v[152:155], v[180:183], v[48:51]
	v_mfma_f32_16x16x32_bf16 v[36:39], v[144:147], v[188:191], v[36:39]
	v_mfma_f32_16x16x32_bf16 v[32:35], v[152:155], v[188:191], v[32:35]
	v_mfma_f32_16x16x32_bf16 v[20:23], v[144:147], v[210:213], v[20:23]
	v_mfma_f32_16x16x32_bf16 v[16:19], v[152:155], v[210:213], v[16:19]
	v_mfma_f32_16x16x32_bf16 v[4:7], v[144:147], v[218:221], v[4:7]
	v_mfma_f32_16x16x32_bf16 v[0:3], v[152:155], v[218:221], v[0:3]
	v_mfma_f32_16x16x32_bf16 v[52:55], v[148:151], v[184:187], v[52:55]
	v_mfma_f32_16x16x32_bf16 v[48:51], v[156:159], v[184:187], v[48:51]
	v_mfma_f32_16x16x32_bf16 v[36:39], v[148:151], v[192:195], v[36:39]
	v_mfma_f32_16x16x32_bf16 v[32:35], v[156:159], v[192:195], v[32:35]
	v_mfma_f32_16x16x32_bf16 v[20:23], v[148:151], v[214:217], v[20:23]
	v_mfma_f32_16x16x32_bf16 v[16:19], v[156:159], v[214:217], v[16:19]
	v_mfma_f32_16x16x32_bf16 v[4:7], v[148:151], v[222:225], v[4:7]
	v_mfma_f32_16x16x32_bf16 v[0:3], v[156:159], v[222:225], v[0:3]
	s_barrier
; #define PG8_STAGE(bufoff, gbase, voff) do { _Pragma("unroll") for (int _i = 0; _i < 2; ++_i) \
;         __builtin_amdgcn_global_load_lds((const unsigned*)((const char*)(gbase) + (voff)[_i]), (LAS unsigned*)(lds + (bufoff) + ldsw + _i * 8192), 16, 0, 0); } while (0)
; #define PG8_LDA(dst, b, h) do { _Pragma("unroll") for (int m = 0; m < 4; ++m) _Pragma("unroll") for (int k = 0; k < 2; ++k) dst[m][k] = *(const LAS bf16x8*)(lds + PG8_SA(b, h) + aoff + m * 2048 + k * 1024); } while (0)
; #define PG8_LDB(dst, b, h) do { _Pragma("unroll") for (int n = 0; n < 2; ++n) _Pragma("unroll") for (int k = 0; k < 2; ++k) dst[n][k] = *(const LAS bf16x8*)(lds + PG8_SB(b, h) + boff + n * 2048 + k * 1024); } while (0)
; #define PG8_MMA(ai, bj, At, Bt) do { __builtin_amdgcn_s_setprio(1); _Pragma("unroll") for (int m = 0; m < 4; ++m) _Pragma("unroll") for (int n = 0; n < 2; ++n) _Pragma("unroll") for (int k = 0; k < 2; ++k) \
;         acc[ai][bj][m][n] = __builtin_amdgcn_mfma_f32_16x16x32_bf16(Bt[n][k], At[m][k], acc[ai][bj][m][n], 0, 0, 0); __builtin_amdgcn_s_setprio(0); } while (0)
; #define PG8_WAIT_V(n) asm volatile("s_waitcnt vmcnt(" #n ")" ::: "memory")
; #define PG8_WAIT_L(n) asm volatile("s_waitcnt lgkmcnt(" #n ")" ::: "memory")
; #define PG8_BAR __builtin_amdgcn_s_barrier()
; #define PG8_SCHED __builtin_amdgcn_sched_barrier(0)
; template <class Epi>
; __device__ __forceinline__ void gemm_phase(LAS unsigned char* lds, const Gemm g, const StaticOrder& S, const Epi& E) {
;     ...
;             PG8_LDB(B0, 1, 0); PG8_LDB(B1, 1, 1); PG8_SCHED; PG8_LDA(At, 1, 0); PG8_STAGE(PG8_SA(0, 1), a2 + hA, voffA);
;             PG8_WAIT_V(8); PG8_WAIT_L(0); PG8_BAR; PG8_MMA(0, 0, At, B0); PG8_MMA(0, 1, At, B1); PG8_BAR; PG8_SCHED;
;             PG8_LDA(At, 1, 1); PG8_STAGE(PG8_SB(1, 0), b3, voffB); PG8_STAGE(PG8_SB(1, 1), b3 + hB, voffB); PG8_STAGE(PG8_SA(1, 0), a3, voffA);
;             PG8_WAIT_V(8); PG8_WAIT_L(0); PG8_BAR; PG8_MMA(1, 0, At, B0); PG8_MMA(1, 1, At, B1); PG8_BAR; PG8_SCHED;
;         }
	ds_read_b128 v[128:131], v240 offset:32768
	ds_read_b128 v[132:135], v240 offset:33792
	ds_read_b128 v[136:139], v240 offset:34816
	ds_read_b128 v[140:143], v240 offset:35840
	ds_read_b128 v[144:147], v240 offset:49152
	ds_read_b128 v[148:151], v240 offset:50176
	ds_read_b128 v[152:155], v240 offset:51200
	ds_read_b128 v[156:159], v240 offset:52224
	ds_read_b128 v[180:183], v209 offset:32768
	ds_read_b128 v[184:187], v209 offset:33792
	ds_read_b128 v[188:191], v209 offset:34816
	ds_read_b128 v[192:195], v209 offset:35840
	ds_read_b128 v[210:213], v209 offset:36864
	ds_read_b128 v[214:217], v209 offset:37888
	ds_read_b128 v[218:221], v209 offset:38912
	ds_read_b128 v[222:225], v209 offset:39936
	s_add_u32 s38, s38, 0x80000
	s_addc_u32 s39, s39, 0
	s_mov_b32 m0, s51
	s_add_i32 s41, 0, 0x18000
	global_load_lds_dwordx4 v160, s[38:39]
	s_mov_b32 m0, s52
	s_nop 0
	global_load_lds_dwordx4 v162, s[38:39]
	s_waitcnt vmcnt(8)
	s_waitcnt lgkmcnt(0)
	s_barrier
	s_waitcnt lgkmcnt(0)
	v_mfma_f32_16x16x32_bf16 v[124:127], v[128:131], v[180:183], v[124:127]
	v_mfma_f32_16x16x32_bf16 v[120:123], v[136:139], v[180:183], v[120:123]
	v_mfma_f32_16x16x32_bf16 v[108:111], v[128:131], v[188:191], v[108:111]
	v_mfma_f32_16x16x32_bf16 v[104:107], v[136:139], v[188:191], v[104:107]
	v_mfma_f32_16x16x32_bf16 v[92:95], v[128:131], v[210:213], v[92:95]
	v_mfma_f32_16x16x32_bf16 v[88:91], v[136:139], v[210:213], v[88:91]
	v_mfma_f32_16x16x32_bf16 v[76:79], v[128:131], v[218:221], v[76:79]
	v_mfma_f32_16x16x32_bf16 v[72:75], v[136:139], v[218:221], v[72:75]
	v_mfma_f32_16x16x32_bf16 v[124:127], v[132:135], v[184:187], v[124:127]
	v_mfma_f32_16x16x32_bf16 v[120:123], v[140:143], v[184:187], v[120:123]
	v_mfma_f32_16x16x32_bf16 v[108:111], v[132:135], v[192:195], v[108:111]
	v_mfma_f32_16x16x32_bf16 v[104:107], v[140:143], v[192:195], v[104:107]
	v_mfma_f32_16x16x32_bf16 v[92:95], v[132:135], v[214:217], v[92:95]
	v_mfma_f32_16x16x32_bf16 v[88:91], v[140:143], v[214:217], v[88:91]
	v_mfma_f32_16x16x32_bf16 v[76:79], v[132:135], v[222:225], v[76:79]
	v_mfma_f32_16x16x32_bf16 v[72:75], v[140:143], v[222:225], v[72:75]
	v_mfma_f32_16x16x32_bf16 v[116:119], v[144:147], v[180:183], v[116:119]
	v_mfma_f32_16x16x32_bf16 v[112:115], v[152:155], v[180:183], v[112:115]
	v_mfma_f32_16x16x32_bf16 v[100:103], v[144:147], v[188:191], v[100:103]
	v_mfma_f32_16x16x32_bf16 v[96:99], v[152:155], v[188:191], v[96:99]
	v_mfma_f32_16x16x32_bf16 v[84:87], v[144:147], v[210:213], v[84:87]
	v_mfma_f32_16x16x32_bf16 v[80:83], v[152:155], v[210:213], v[80:83]
	v_mfma_f32_16x16x32_bf16 v[68:71], v[144:147], v[218:221], v[68:71]
	v_mfma_f32_16x16x32_bf16 v[64:67], v[152:155], v[218:221], v[64:67]
	v_mfma_f32_16x16x32_bf16 v[116:119], v[148:151], v[184:187], v[116:119]
	v_mfma_f32_16x16x32_bf16 v[112:115], v[156:159], v[184:187], v[112:115]
	v_mfma_f32_16x16x32_bf16 v[100:103], v[148:151], v[192:195], v[100:103]
	v_mfma_f32_16x16x32_bf16 v[96:99], v[156:159], v[192:195], v[96:99]
	v_mfma_f32_16x16x32_bf16 v[84:87], v[148:151], v[214:217], v[84:87]
	v_mfma_f32_16x16x32_bf16 v[80:83], v[156:159], v[214:217], v[80:83]
	v_mfma_f32_16x16x32_bf16 v[68:71], v[148:151], v[222:225], v[68:71]
	v_mfma_f32_16x16x32_bf16 v[64:67], v[156:159], v[222:225], v[64:67]
	s_barrier
	ds_read_b128 v[180:183], v209 offset:49152
	ds_read_b128 v[184:187], v209 offset:50176
	ds_read_b128 v[188:191], v209 offset:51200
	ds_read_b128 v[192:195], v209 offset:52224
	ds_read_b128 v[210:213], v209 offset:53248
	ds_read_b128 v[214:217], v209 offset:54272
	ds_read_b128 v[218:221], v209 offset:55296
	ds_read_b128 v[222:225], v209 offset:56320
	s_add_i32 s41, s41, s48
	s_add_i32 m0, s41, 0x4000
	s_nop 0
	global_load_lds_dwordx4 v241, s[68:69]
	s_add_i32 m0, s41, 0x6000
	s_nop 0
	global_load_lds_dwordx4 v242, s[68:69]
	s_sub_u32 s68, s68, s46
	s_subb_u32 s69, s69, 0
	s_mov_b32 m0, s41
	s_nop 0
	global_load_lds_dwordx4 v241, s[68:69]
	s_add_i32 m0, s41, 0x2000
	s_nop 0
	global_load_lds_dwordx4 v242, s[68:69]
	s_sub_u32 s38, s38, 0x80000
	s_subb_u32 s39, s39, 0
	s_mov_b32 m0, s55
	s_nop 0
	global_load_lds_dwordx4 v243, s[38:39]
	s_mov_b32 m0, s56
	s_nop 0
	global_load_lds_dwordx4 v244, s[38:39]
	s_waitcnt vmcnt(8)
	s_waitcnt lgkmcnt(0)
	s_barrier
	s_waitcnt lgkmcnt(0)
	v_mfma_f32_16x16x32_bf16 v[60:63], v[128:131], v[180:183], v[60:63]
	v_mfma_f32_16x16x32_bf16 v[56:59], v[136:139], v[180:183], v[56:59]
	v_mfma_f32_16x16x32_bf16 v[44:47], v[128:131], v[188:191], v[44:47]
	v_mfma_f32_16x16x32_bf16 v[40:43], v[136:139], v[188:191], v[40:43]
	v_mfma_f32_16x16x32_bf16 v[28:31], v[128:131], v[210:213], v[28:31]
	v_mfma_f32_16x16x32_bf16 v[24:27], v[136:139], v[210:213], v[24:27]
	v_mfma_f32_16x16x32_bf16 v[12:15], v[128:131], v[218:221], v[12:15]
	v_mfma_f32_16x16x32_bf16 v[8:11], v[136:139], v[218:221], v[8:11]
	v_mfma_f32_16x16x32_bf16 v[60:63], v[132:135], v[184:187], v[60:63]
	v_mfma_f32_16x16x32_bf16 v[56:59], v[140:143], v[184:187], v[56:59]
	v_mfma_f32_16x16x32_bf16 v[44:47], v[132:135], v[192:195], v[44:47]
	v_mfma_f32_16x16x32_bf16 v[40:43], v[140:143], v[192:195], v[40:43]
	v_mfma_f32_16x16x32_bf16 v[28:31], v[132:135], v[214:217], v[28:31]
	v_mfma_f32_16x16x32_bf16 v[24:27], v[140:143], v[214:217], v[24:27]
	v_mfma_f32_16x16x32_bf16 v[12:15], v[132:135], v[222:225], v[12:15]
	v_mfma_f32_16x16x32_bf16 v[8:11], v[140:143], v[222:225], v[8:11]
	v_mfma_f32_16x16x32_bf16 v[52:55], v[144:147], v[180:183], v[52:55]
	v_mfma_f32_16x16x32_bf16 v[48:51], v[152:155], v[180:183], v[48:51]
	v_mfma_f32_16x16x32_bf16 v[36:39], v[144:147], v[188:191], v[36:39]
	v_mfma_f32_16x16x32_bf16 v[32:35], v[152:155], v[188:191], v[32:35]
	v_mfma_f32_16x16x32_bf16 v[20:23], v[144:147], v[210:213], v[20:23]
	v_mfma_f32_16x16x32_bf16 v[16:19], v[152:155], v[210:213], v[16:19]
	v_mfma_f32_16x16x32_bf16 v[4:7], v[144:147], v[218:221], v[4:7]
	v_mfma_f32_16x16x32_bf16 v[0:3], v[152:155], v[218:221], v[0:3]
	v_mfma_f32_16x16x32_bf16 v[52:55], v[148:151], v[184:187], v[52:55]
	v_mfma_f32_16x16x32_bf16 v[48:51], v[156:159], v[184:187], v[48:51]
	v_mfma_f32_16x16x32_bf16 v[36:39], v[148:151], v[192:195], v[36:39]
	v_mfma_f32_16x16x32_bf16 v[32:35], v[156:159], v[192:195], v[32:35]
	v_mfma_f32_16x16x32_bf16 v[20:23], v[148:151], v[214:217], v[20:23]
	v_mfma_f32_16x16x32_bf16 v[16:19], v[156:159], v[214:217], v[16:19]
	v_mfma_f32_16x16x32_bf16 v[4:7], v[148:151], v[222:225], v[4:7]
	v_mfma_f32_16x16x32_bf16 v[0:3], v[156:159], v[222:225], v[0:3]
	s_barrier
	s_add_u32 s0, s0, 0x100
	s_addc_u32 s1, s1, 0
	s_add_u32 s29, s29, 0x100
	s_addc_u32 s33, s33, 0
	s_cmp_ge_u32 s40, s54
	s_mov_b32 s37, s40
	s_cbranch_scc0 .LBB0_431
	s_and_b64 vcc, exec, s[24:25]
	s_cbranch_vccz .LBB0_434
	s_barrier
